# v7
# baseline (speedup 1.0000x reference)
; __device__ __forceinline__ void phase_prep(const Params& p, char* shm) {
;   const int tid = threadIdx.x; const long gtid = blockIdx.x * (long)NTHR + tid, gstride = gridDim.x * (long)NTHR;
;   float* ssq = (float*)(p.ws + OFF_SSQ);
;   for (long i = gtid; i < 5L * T_TOK; i += gstride) ssq[i] = 0.f;
;   float* cosT = (float*)(p.ws + OFF_COS); float* sinT = (float*)(p.ws + OFF_SIN);
;   for (long i = gtid; i < 16384L * 32; i += gstride) {
;     const int pos = (int)(i >> 5), j = (int)(i & 31);
;     double inv = 0.0;
; #pragma unroll
;     for (int e = 0; e < 32; ++e) inv = (j == e) ? p.inv_freq[e] : inv;
;     const double rev = (double)pos * inv * 0.15915494309189535;
;     const float fr = (float)(rev - rint(rev));
;     cosT[i] = __builtin_amdgcn_cosf(fr); sinT[i] = __builtin_amdgcn_sinf(fr);
;   }
;   u16* wsb = (u16*)(p.ws + OFF_WS);
;   for (long i = gtid; i < 8L * 128 * 128; i += gstride) wsb[i] = f2bf(p.w_s[i]);
;   {
;     u16* xb = (u16*)(p.ws + OFF_XB); float* rstd1 = (float*)(p.ws + OFF_RSTD1);
;     const int wid = tid >> 6, lane = tid & 63;
;     for (int rowq = (blockIdx.x * 8 + wid) * 4; rowq < T_TOK; rowq += gridDim.x * 32) {
;       float4 va[4][2], vb[4][2];
; #pragma unroll
;       for (int r = 0; r < 4; ++r) {
;         const int row = rowq + r; const float* src = row < TP ? p.xp + (long)row * DM : p.xs + (long)(row - TP) * DM;
; #pragma unroll
;         for (int i = 0; i < 2; ++i) { va[r][i] = *(const float4*)(src + i * 512 + lane * 8); vb[r][i] = *(const float4*)(src + i * 512 + lane * 8 + 4); }
;       }
; #pragma unroll
;       for (int r = 0; r < 4; ++r) {
;         const int row = rowq + r; float s = 0.f;
; #pragma unroll
;         for (int i = 0; i < 2; ++i) {
;           const float4 a = va[r][i], b = vb[r][i];
;           s += a.x * a.x + a.y * a.y + a.z * a.z + a.w * a.w + b.x * b.x + b.y * b.y + b.z * b.z + b.w * b.w;
;           u32x4 w = {cvtpk(a.x, a.y), cvtpk(a.z, a.w), cvtpk(b.x, b.y), cvtpk(b.z, b.w)};
;           *(u32x4*)(xb + (long)row * DM + i * 512 + lane * 8) = w;
;         }
;         s += __shfl_xor(s, 1); s += __shfl_xor(s, 2); s += __shfl_xor(s, 4); s += __shfl_xor(s, 8); s += __shfl_xor(s, 16); s += __shfl_xor(s, 32);
;         if (lane == 0) rstd1[row] = rsqrtf(s * (1.f / DM) + EPS);
;       }
;     }
;   }
;   prep_wT(p.w_in, 1024, 4800, (u16*)(p.ws + OFF_WIN), NZ / 64, p.norm_mix_g, true, shm);
.LBB0_14:
	v_readfirstlane_b32 s99, v200
	s_nop 3
	s_cmp_ge_u32 s99, 0x100
	s_cbranch_scc0 .Lnoprio0
	s_setprio 1
